# attention unit epilogue: map-1 waves hand over raw O plus 1/l, map-0 combine uses two scalar VALU per element instead of packed pairs with pairing moves
# baseline (speedup 1.0000x reference)
.Lmy_epi_noload:
	ds_bpermute_b32 v2, v197, v168
	v_lshlrev_b64 v[4:5], 10, v[182:183]
	s_lshl_b32 s4, s78, 7
	s_waitcnt lgkmcnt(0)
	v_add_f32_e32 v2, v168, v2
	v_div_scale_f32 v6, s[56:57], v2, v2, 1.0
	v_rcp_f32_e32 v7, v6
	v_div_scale_f32 v8, vcc, 1.0, v2, 1.0
	v_fma_f32 v9, -v6, v7, 1.0
	v_fmac_f32_e32 v7, v9, v7
	v_mul_f32_e32 v9, v8, v7
	v_fma_f32 v10, -v6, v9, v8
	v_fmac_f32_e32 v9, v10, v7
	v_fma_f32 v6, -v6, v9, v8
	v_div_fmas_f32 v6, v6, v7, v9
	s_andn2_b64 vcc, exec, s[12:13]
	v_div_fixup_f32 v6, v6, v2, 1.0
	s_cbranch_vccnz .LBB0_561
	v_subrev_u32_e32 v2, 0x12800, v211
	v_lshrrev_b32_e32 v7, 14, v2
	v_and_b32_e32 v2, 0xff, v2
	v_lshl_add_u32 v2, v7, 8, v2
	v_add_u32_e32 v2, 0x22b00, v2
	ds_write_b32 v2, v6
	ds_write2st64_b32 v211, v66, v67 offset1:1
	ds_write2st64_b32 v211, v68, v69 offset0:2 offset1:3
	ds_write2st64_b32 v211, v70, v71 offset0:4 offset1:5
	ds_write2st64_b32 v211, v72, v73 offset0:6 offset1:7
	ds_write2st64_b32 v211, v74, v75 offset0:8 offset1:9
	ds_write2st64_b32 v211, v76, v77 offset0:10 offset1:11
	ds_write2st64_b32 v211, v78, v79 offset0:12 offset1:13
	ds_write2st64_b32 v211, v80, v81 offset0:14 offset1:15
	ds_write2st64_b32 v211, v50, v51 offset0:16 offset1:17
	ds_write2st64_b32 v211, v52, v53 offset0:18 offset1:19
	ds_write2st64_b32 v211, v54, v55 offset0:20 offset1:21
	ds_write2st64_b32 v211, v56, v57 offset0:22 offset1:23
	ds_write2st64_b32 v211, v58, v59 offset0:24 offset1:25
	ds_write2st64_b32 v211, v60, v61 offset0:26 offset1:27
	ds_write2st64_b32 v211, v62, v63 offset0:28 offset1:29
	ds_write2st64_b32 v211, v64, v65 offset0:30 offset1:31
	ds_write2st64_b32 v211, v34, v35 offset0:32 offset1:33
	ds_write2st64_b32 v211, v36, v37 offset0:34 offset1:35
	ds_write2st64_b32 v211, v38, v39 offset0:36 offset1:37
	ds_write2st64_b32 v211, v40, v41 offset0:38 offset1:39
	ds_write2st64_b32 v211, v42, v43 offset0:40 offset1:41
	ds_write2st64_b32 v211, v44, v45 offset0:42 offset1:43
	ds_write2st64_b32 v211, v46, v47 offset0:44 offset1:45
	ds_write2st64_b32 v211, v48, v49 offset0:46 offset1:47
	ds_write2st64_b32 v211, v18, v19 offset0:48 offset1:49
	ds_write2st64_b32 v211, v20, v21 offset0:50 offset1:51
	ds_write2st64_b32 v211, v22, v23 offset0:52 offset1:53
	ds_write2st64_b32 v211, v24, v25 offset0:54 offset1:55
	ds_write2st64_b32 v211, v26, v27 offset0:56 offset1:57
	ds_write2st64_b32 v211, v28, v29 offset0:58 offset1:59
	ds_write2st64_b32 v211, v30, v31 offset0:60 offset1:61
	ds_write2st64_b32 v211, v32, v33 offset0:62 offset1:63
.LBB0_561:
	s_andn2_b64 vcc, exec, s[10:11]
	s_waitcnt lgkmcnt(0)
	s_barrier
	s_cbranch_vccnz .LBB0_563
	v_or_b32_e32 v4, s4, v4
	v_subrev_u32_e32 v247, 0x12800, v211
	v_lshrrev_b32_e32 v246, 14, v247
	v_and_b32_e32 v247, 0xff, v247
	v_lshl_add_u32 v247, v246, 8, v247
	v_add_u32_e32 v247, 0x22b00, v247
	ds_read_b32 v247, v247
	ds_read2st64_b32 v[82:83], v211 offset1:1
	ds_read2st64_b32 v[84:85], v211 offset0:2 offset1:3
	ds_read2st64_b32 v[86:87], v211 offset0:4 offset1:5
	ds_read2st64_b32 v[240:241], v211 offset0:6 offset1:7
	ds_read2st64_b32 v[248:249], v211 offset0:8 offset1:9
	ds_read2st64_b32 v[250:251], v211 offset0:10 offset1:11
	ds_read2st64_b32 v[252:253], v211 offset0:12 offset1:13
	ds_read2st64_b32 v[254:255], v211 offset0:14 offset1:15
	s_waitcnt lgkmcnt(8)
	v_mul_f32_e32 v247, v169, v247
	s_waitcnt lgkmcnt(7)
	v_mul_f32_e32 v13, v6, v66
	v_fma_f32 v13, -v247, v82, v13
	v_mul_f32_e32 v246, v13, v13
	v_mul_f32_e32 v14, v6, v67
	v_fma_f32 v14, -v247, v83, v14
	v_fmac_f32_e32 v246, v14, v14
	ds_read2st64_b32 v[82:83], v211 offset0:16 offset1:17
	s_waitcnt lgkmcnt(7)
	v_mul_f32_e32 v8, v6, v68
	v_fma_f32 v8, -v247, v84, v8
	v_fmac_f32_e32 v246, v8, v8
	v_mul_f32_e32 v9, v6, v69
	v_fma_f32 v9, -v247, v85, v9
	v_fmac_f32_e32 v246, v9, v9
	ds_read2st64_b32 v[84:85], v211 offset0:18 offset1:19
	s_waitcnt lgkmcnt(7)
	v_mul_f32_e32 v2, v6, v70
	v_fma_f32 v2, -v247, v86, v2
	v_fmac_f32_e32 v246, v2, v2
	v_mul_f32_e32 v10, v6, v71
	v_fma_f32 v10, -v247, v87, v10
	v_fmac_f32_e32 v246, v10, v10
	ds_read2st64_b32 v[86:87], v211 offset0:20 offset1:21
	s_waitcnt lgkmcnt(7)
	v_mul_f32_e32 v11, v6, v72
	v_fma_f32 v11, -v247, v240, v11
	v_fmac_f32_e32 v246, v11, v11
	v_mul_f32_e32 v12, v6, v73
	v_fma_f32 v12, -v247, v241, v12
	v_fmac_f32_e32 v246, v12, v12
	ds_read2st64_b32 v[240:241], v211 offset0:22 offset1:23
	s_waitcnt lgkmcnt(7)
	v_mul_f32_e32 v69, v6, v74
	v_fma_f32 v69, -v247, v248, v69
	v_fmac_f32_e32 v246, v69, v69
	v_mul_f32_e32 v70, v6, v75
	v_fma_f32 v70, -v247, v249, v70
	v_fmac_f32_e32 v246, v70, v70
	ds_read2st64_b32 v[248:249], v211 offset0:24 offset1:25
	s_waitcnt lgkmcnt(7)
	v_mul_f32_e32 v67, v6, v76
	v_fma_f32 v67, -v247, v250, v67
	v_fmac_f32_e32 v246, v67, v67
	v_mul_f32_e32 v68, v6, v77
	v_fma_f32 v68, -v247, v251, v68
	v_fmac_f32_e32 v246, v68, v68
	ds_read2st64_b32 v[250:251], v211 offset0:26 offset1:27
	s_waitcnt lgkmcnt(7)
	v_mul_f32_e32 v15, v6, v78
	v_fma_f32 v15, -v247, v252, v15
	v_fmac_f32_e32 v246, v15, v15
	v_mul_f32_e32 v16, v6, v79
	v_fma_f32 v16, -v247, v253, v16
	v_fmac_f32_e32 v246, v16, v16
	ds_read2st64_b32 v[252:253], v211 offset0:28 offset1:29
	s_waitcnt lgkmcnt(7)
	v_mul_f32_e32 v17, v6, v80
	v_fma_f32 v17, -v247, v254, v17
	v_fmac_f32_e32 v246, v17, v17
	v_mul_f32_e32 v66, v6, v81
	v_fma_f32 v66, -v247, v255, v66
	v_fmac_f32_e32 v246, v66, v66
	ds_read2st64_b32 v[254:255], v211 offset0:30 offset1:31
	s_waitcnt lgkmcnt(7)
	v_mul_f32_e32 v73, v6, v50
	v_fma_f32 v73, -v247, v82, v73
	v_fmac_f32_e32 v246, v73, v73
	v_mul_f32_e32 v74, v6, v51
	v_fma_f32 v74, -v247, v83, v74
	v_fmac_f32_e32 v246, v74, v74
	ds_read2st64_b32 v[82:83], v211 offset0:32 offset1:33
	s_waitcnt lgkmcnt(7)
	v_mul_f32_e32 v71, v6, v52
	v_fma_f32 v71, -v247, v84, v71
	v_fmac_f32_e32 v246, v71, v71
	v_mul_f32_e32 v72, v6, v53
	v_fma_f32 v72, -v247, v85, v72
	v_fmac_f32_e32 v246, v72, v72
	ds_read2st64_b32 v[84:85], v211 offset0:34 offset1:35
	s_waitcnt lgkmcnt(7)
	v_mul_f32_e32 v50, v6, v54
	v_fma_f32 v50, -v247, v86, v50
	v_fmac_f32_e32 v246, v50, v50
	v_mul_f32_e32 v51, v6, v55
	v_fma_f32 v51, -v247, v87, v51
	v_fmac_f32_e32 v246, v51, v51
	ds_read2st64_b32 v[86:87], v211 offset0:36 offset1:37
	s_waitcnt lgkmcnt(7)
	v_mul_f32_e32 v52, v6, v56
	v_fma_f32 v52, -v247, v240, v52
	v_fmac_f32_e32 v246, v52, v52
	v_mul_f32_e32 v53, v6, v57
	v_fma_f32 v53, -v247, v241, v53
	v_fmac_f32_e32 v246, v53, v53
	ds_read2st64_b32 v[240:241], v211 offset0:38 offset1:39
	s_waitcnt lgkmcnt(7)
	v_mul_f32_e32 v75, v6, v58
	v_fma_f32 v75, -v247, v248, v75
	v_fmac_f32_e32 v246, v75, v75
	v_mul_f32_e32 v76, v6, v59
	v_fma_f32 v76, -v247, v249, v76
	v_fmac_f32_e32 v246, v76, v76
	ds_read2st64_b32 v[248:249], v211 offset0:40 offset1:41
	s_waitcnt lgkmcnt(7)
	v_mul_f32_e32 v58, v6, v60
	v_fma_f32 v58, -v247, v250, v58
	v_fmac_f32_e32 v246, v58, v58
	v_mul_f32_e32 v59, v6, v61
	v_fma_f32 v59, -v247, v251, v59
	v_fmac_f32_e32 v246, v59, v59
	ds_read2st64_b32 v[250:251], v211 offset0:42 offset1:43
	s_waitcnt lgkmcnt(7)
	v_mul_f32_e32 v54, v6, v62
	v_fma_f32 v54, -v247, v252, v54
	v_fmac_f32_e32 v246, v54, v54
	v_mul_f32_e32 v55, v6, v63
	v_fma_f32 v55, -v247, v253, v55
	v_fmac_f32_e32 v246, v55, v55
	ds_read2st64_b32 v[252:253], v211 offset0:44 offset1:45
	s_waitcnt lgkmcnt(7)
	v_mul_f32_e32 v56, v6, v64
	v_fma_f32 v56, -v247, v254, v56
	v_fmac_f32_e32 v246, v56, v56
	v_mul_f32_e32 v57, v6, v65
	v_fma_f32 v57, -v247, v255, v57
	v_fmac_f32_e32 v246, v57, v57
	ds_read2st64_b32 v[254:255], v211 offset0:46 offset1:47
	s_waitcnt lgkmcnt(7)
	v_mul_f32_e32 v62, v6, v34
	v_fma_f32 v62, -v247, v82, v62
	v_fmac_f32_e32 v246, v62, v62
	v_mul_f32_e32 v63, v6, v35
	v_fma_f32 v63, -v247, v83, v63
	v_fmac_f32_e32 v246, v63, v63
	ds_read2st64_b32 v[82:83], v211 offset0:48 offset1:49
	s_waitcnt lgkmcnt(7)
	v_mul_f32_e32 v60, v6, v36
	v_fma_f32 v60, -v247, v84, v60
	v_fmac_f32_e32 v246, v60, v60
	v_mul_f32_e32 v61, v6, v37
	v_fma_f32 v61, -v247, v85, v61
	v_fmac_f32_e32 v246, v61, v61
	ds_read2st64_b32 v[84:85], v211 offset0:50 offset1:51
	s_waitcnt lgkmcnt(7)
	v_mul_f32_e32 v34, v6, v38
	v_fma_f32 v34, -v247, v86, v34
	v_fmac_f32_e32 v246, v34, v34
	v_mul_f32_e32 v35, v6, v39
	v_fma_f32 v35, -v247, v87, v35
	v_fmac_f32_e32 v246, v35, v35
	ds_read2st64_b32 v[86:87], v211 offset0:52 offset1:53
	s_waitcnt lgkmcnt(7)
	v_mul_f32_e32 v36, v6, v40
	v_fma_f32 v36, -v247, v240, v36
	v_fmac_f32_e32 v246, v36, v36
	v_mul_f32_e32 v37, v6, v41
	v_fma_f32 v37, -v247, v241, v37
	v_fmac_f32_e32 v246, v37, v37
	ds_read2st64_b32 v[240:241], v211 offset0:54 offset1:55
	s_waitcnt lgkmcnt(7)
	v_mul_f32_e32 v64, v6, v42
	v_fma_f32 v64, -v247, v248, v64
	v_fmac_f32_e32 v246, v64, v64
	v_mul_f32_e32 v65, v6, v43
	v_fma_f32 v65, -v247, v249, v65
	v_fmac_f32_e32 v246, v65, v65
	ds_read2st64_b32 v[248:249], v211 offset0:56 offset1:57
	s_waitcnt lgkmcnt(7)
	v_mul_f32_e32 v42, v6, v44
	v_fma_f32 v42, -v247, v250, v42
	v_fmac_f32_e32 v246, v42, v42
	v_mul_f32_e32 v43, v6, v45
	v_fma_f32 v43, -v247, v251, v43
	v_fmac_f32_e32 v246, v43, v43
	ds_read2st64_b32 v[250:251], v211 offset0:58 offset1:59
	s_waitcnt lgkmcnt(7)
	v_mul_f32_e32 v38, v6, v46
	v_fma_f32 v38, -v247, v252, v38
	v_fmac_f32_e32 v246, v38, v38
	v_mul_f32_e32 v39, v6, v47
	v_fma_f32 v39, -v247, v253, v39
	v_fmac_f32_e32 v246, v39, v39
	ds_read2st64_b32 v[252:253], v211 offset0:60 offset1:61
	s_waitcnt lgkmcnt(7)
	v_mul_f32_e32 v40, v6, v48
	v_fma_f32 v40, -v247, v254, v40
	v_fmac_f32_e32 v246, v40, v40
	v_mul_f32_e32 v41, v6, v49
	v_fma_f32 v41, -v247, v255, v41
	v_fmac_f32_e32 v246, v41, v41
	ds_read2st64_b32 v[254:255], v211 offset0:62 offset1:63
	s_waitcnt lgkmcnt(7)
	v_mul_f32_e32 v46, v6, v18
	v_fma_f32 v46, -v247, v82, v46
	v_fmac_f32_e32 v246, v46, v46
	v_mul_f32_e32 v47, v6, v19
	v_fma_f32 v47, -v247, v83, v47
	v_fmac_f32_e32 v246, v47, v47
	s_waitcnt lgkmcnt(6)
	v_mul_f32_e32 v44, v6, v20
	v_fma_f32 v44, -v247, v84, v44
	v_fmac_f32_e32 v246, v44, v44
	v_mul_f32_e32 v45, v6, v21
	v_fma_f32 v45, -v247, v85, v45
	v_fmac_f32_e32 v246, v45, v45
	s_waitcnt lgkmcnt(5)
	v_mul_f32_e32 v18, v6, v22
	v_fma_f32 v18, -v247, v86, v18
	v_fmac_f32_e32 v246, v18, v18
	v_mul_f32_e32 v19, v6, v23
	v_fma_f32 v19, -v247, v87, v19
	v_fmac_f32_e32 v246, v19, v19
	s_waitcnt lgkmcnt(4)
	v_mul_f32_e32 v20, v6, v24
	v_fma_f32 v20, -v247, v240, v20
	v_fmac_f32_e32 v246, v20, v20
	v_mul_f32_e32 v21, v6, v25
	v_fma_f32 v21, -v247, v241, v21
	v_fmac_f32_e32 v246, v21, v21
	s_waitcnt lgkmcnt(3)
	v_mul_f32_e32 v26, v6, v26
	v_fma_f32 v26, -v247, v248, v26
	v_fmac_f32_e32 v246, v26, v26
	v_mul_f32_e32 v27, v6, v27
	v_fma_f32 v27, -v247, v249, v27
	v_fmac_f32_e32 v246, v27, v27
	s_waitcnt lgkmcnt(2)
	v_mul_f32_e32 v24, v6, v28
	v_fma_f32 v24, -v247, v250, v24
	v_fmac_f32_e32 v246, v24, v24
	v_mul_f32_e32 v25, v6, v29
	v_fma_f32 v25, -v247, v251, v25
	v_fmac_f32_e32 v246, v25, v25
	s_waitcnt lgkmcnt(1)
	v_mul_f32_e32 v22, v6, v30
	v_fma_f32 v22, -v247, v252, v22
	v_fmac_f32_e32 v246, v22, v22
	v_mul_f32_e32 v23, v6, v31
	v_fma_f32 v23, -v247, v253, v23
	v_fmac_f32_e32 v246, v23, v23
	s_waitcnt lgkmcnt(0)
	v_mul_f32_e32 v7, v6, v33
	v_fma_f32 v7, -v247, v255, v7
	v_fmac_f32_e32 v246, v7, v7
	v_mul_f32_e32 v6, v6, v32
	v_fma_f32 v6, -v247, v254, v6
	v_fmac_f32_e32 v246, v6, v6
	v_lshlrev_b64 v[48:49], 1, v[4:5]
	v_mov_b32_e32 v32, v246
	v_lshlrev_b32_e32 v246, 1, v242
	v_add_u32_e32 v246, 0x22900, v246
	ds_read_b128 v[88:91], v246 offset:0
	ds_read_b128 v[92:95], v246 offset:32
	ds_read_b128 v[96:99], v246 offset:64
	ds_read_b128 v[100:103], v246 offset:96
	ds_read_b128 v[104:107], v246 offset:128
	ds_read_b128 v[108:111], v246 offset:160
	ds_read_b128 v[112:115], v246 offset:192
	ds_read_b128 v[116:119], v246 offset:224
	ds_read_b128 v[120:123], v246 offset:256
	ds_read_b128 v[124:127], v246 offset:288
	ds_read_b128 v[128:131], v246 offset:320
	ds_read_b128 v[132:135], v246 offset:352
	ds_read_b128 v[136:139], v246 offset:384
	ds_read_b128 v[140:143], v246 offset:416
	ds_read_b128 v[144:147], v246 offset:448
	ds_read_b128 v[148:151], v246 offset:480
	ds_bpermute_b32 v33, v197, v32
	s_waitcnt lgkmcnt(0)
	v_add_f32_e32 v32, v32, v33
	v_fmamk_f32 v32, v32, 0x3c000000, v214
	v_mul_f32_e32 v33, 0x4f800000, v32
	v_cmp_gt_f32_e32 vcc, s71, v32
	s_nop 1
	v_cndmask_b32_e32 v32, v32, v33, vcc
	v_sqrt_f32_e32 v33, v32
	s_nop 0
	v_add_u32_e32 v77, -1, v33
	v_fma_f32 v80, -v77, v33, v32
	v_cmp_ge_f32_e64 s[4:5], 0, v80
	v_add_u32_e32 v80, 1, v33
	s_nop 0
	v_cndmask_b32_e64 v77, v33, v77, s[4:5]
	v_fma_f32 v33, -v80, v33, v32
	v_cmp_lt_f32_e64 s[4:5], 0, v33
	s_nop 1
	v_cndmask_b32_e64 v33, v77, v80, s[4:5]
	v_mul_f32_e32 v77, 0x37800000, v33
	v_cndmask_b32_e32 v33, v33, v77, vcc
	v_cmp_class_f32_e32 vcc, v32, v200
	s_nop 1
	v_cndmask_b32_e32 v32, v33, v32, vcc
	v_div_scale_f32 v33, s[4:5], v32, v32, s76
	v_rcp_f32_e32 v77, v33
	s_nop 0
	v_fma_f32 v80, -v33, v77, 1.0
	v_fmac_f32_e32 v77, v80, v77
	v_div_scale_f32 v80, vcc, s76, v32, s76
	v_mul_f32_e32 v81, v80, v77
	v_fma_f32 v82, -v33, v81, v80
	v_fmac_f32_e32 v81, v82, v77
	v_fma_f32 v33, -v33, v81, v80
	v_div_fmas_f32 v33, v33, v77, v81
	v_div_fixup_f32 v77, v33, v32, s76
	v_lshl_add_u64 v[244:245], v[176:177], 0, v[48:49]
	v_lshl_add_u64 v[244:245], v[244:245], 0, v[242:243]
	s_waitcnt vmcnt(7)
	v_permlane32_swap_b32_e32 v152, v154
	v_permlane32_swap_b32_e32 v153, v155
	v_mul_f32_e32 v13, v13, v77
	v_mul_f32_e32 v14, v14, v77
	v_lshlrev_b32_e32 v247, 16, v152
	v_mul_f32_e32 v13, v88, v13
	v_mul_f32_e32 v14, v89, v14
	v_and_b32_e32 v152, 0xffff0000, v152
	v_mul_f32_e32 v13, v13, v247
	v_mul_f32_e32 v14, v14, v152
	v_cvt_pk_bf16_f32 v152, v13, v14
	v_mul_f32_e32 v8, v8, v77
	v_mul_f32_e32 v9, v9, v77
	v_lshlrev_b32_e32 v247, 16, v153
	v_mul_f32_e32 v8, v90, v8
	v_mul_f32_e32 v9, v91, v9
	v_and_b32_e32 v153, 0xffff0000, v153
	v_mul_f32_e32 v8, v8, v247
	v_mul_f32_e32 v9, v9, v153
	v_cvt_pk_bf16_f32 v153, v8, v9
	v_mul_f32_e32 v2, v2, v77
	v_mul_f32_e32 v10, v10, v77
	v_lshlrev_b32_e32 v247, 16, v154
	v_mul_f32_e32 v2, v92, v2
	v_mul_f32_e32 v10, v93, v10
	v_and_b32_e32 v154, 0xffff0000, v154
	v_mul_f32_e32 v2, v2, v247
	v_mul_f32_e32 v10, v10, v154
	v_cvt_pk_bf16_f32 v154, v2, v10
	v_mul_f32_e32 v11, v11, v77
	v_mul_f32_e32 v12, v12, v77
	v_lshlrev_b32_e32 v247, 16, v155
	v_mul_f32_e32 v11, v94, v11
	v_mul_f32_e32 v12, v95, v12
	v_and_b32_e32 v155, 0xffff0000, v155
	v_mul_f32_e32 v11, v11, v247
	v_mul_f32_e32 v12, v12, v155
	v_cvt_pk_bf16_f32 v155, v11, v12
	s_nop 1
	v_permlane32_swap_b32_e32 v152, v154
	v_permlane32_swap_b32_e32 v153, v155
	global_store_dwordx4 v[244:245], v[152:155], off offset:0
	s_waitcnt vmcnt(7)
	v_permlane32_swap_b32_e32 v156, v158
	v_permlane32_swap_b32_e32 v157, v159
	v_mul_f32_e32 v69, v69, v77
	v_mul_f32_e32 v70, v70, v77
	v_lshlrev_b32_e32 v247, 16, v156
	v_mul_f32_e32 v69, v96, v69
	v_mul_f32_e32 v70, v97, v70
	v_and_b32_e32 v156, 0xffff0000, v156
	v_mul_f32_e32 v69, v69, v247
	v_mul_f32_e32 v70, v70, v156
	v_cvt_pk_bf16_f32 v156, v69, v70
	v_mul_f32_e32 v67, v67, v77
	v_mul_f32_e32 v68, v68, v77
	v_lshlrev_b32_e32 v247, 16, v157
	v_mul_f32_e32 v67, v98, v67
	v_mul_f32_e32 v68, v99, v68
	v_and_b32_e32 v157, 0xffff0000, v157
	v_mul_f32_e32 v67, v67, v247
	v_mul_f32_e32 v68, v68, v157
	v_cvt_pk_bf16_f32 v157, v67, v68
	v_mul_f32_e32 v15, v15, v77
	v_mul_f32_e32 v16, v16, v77
	v_lshlrev_b32_e32 v247, 16, v158
	v_mul_f32_e32 v15, v100, v15
	v_mul_f32_e32 v16, v101, v16
	v_and_b32_e32 v158, 0xffff0000, v158
	v_mul_f32_e32 v15, v15, v247
	v_mul_f32_e32 v16, v16, v158
	v_cvt_pk_bf16_f32 v158, v15, v16
	v_mul_f32_e32 v17, v17, v77
	v_mul_f32_e32 v66, v66, v77
	v_lshlrev_b32_e32 v247, 16, v159
	v_mul_f32_e32 v17, v102, v17
	v_mul_f32_e32 v66, v103, v66
	v_and_b32_e32 v159, 0xffff0000, v159
	v_mul_f32_e32 v17, v17, v247
	v_mul_f32_e32 v66, v66, v159
	v_cvt_pk_bf16_f32 v159, v17, v66
	s_nop 1
	v_permlane32_swap_b32_e32 v156, v158
	v_permlane32_swap_b32_e32 v157, v159
	global_store_dwordx4 v[244:245], v[156:159], off offset:32
	s_waitcnt vmcnt(7)
	v_permlane32_swap_b32_e32 v160, v162
	v_permlane32_swap_b32_e32 v161, v163
	v_mul_f32_e32 v73, v73, v77
	v_mul_f32_e32 v74, v74, v77
	v_lshlrev_b32_e32 v247, 16, v160
	v_mul_f32_e32 v73, v104, v73
	v_mul_f32_e32 v74, v105, v74
	v_and_b32_e32 v160, 0xffff0000, v160
	v_mul_f32_e32 v73, v73, v247
	v_mul_f32_e32 v74, v74, v160
	v_cvt_pk_bf16_f32 v160, v73, v74
	v_mul_f32_e32 v71, v71, v77
	v_mul_f32_e32 v72, v72, v77
	v_lshlrev_b32_e32 v247, 16, v161
	v_mul_f32_e32 v71, v106, v71
	v_mul_f32_e32 v72, v107, v72
	v_and_b32_e32 v161, 0xffff0000, v161
	v_mul_f32_e32 v71, v71, v247
	v_mul_f32_e32 v72, v72, v161
	v_cvt_pk_bf16_f32 v161, v71, v72
	v_mul_f32_e32 v50, v50, v77
	v_mul_f32_e32 v51, v51, v77
	v_lshlrev_b32_e32 v247, 16, v162
	v_mul_f32_e32 v50, v108, v50
	v_mul_f32_e32 v51, v109, v51
	v_and_b32_e32 v162, 0xffff0000, v162
	v_mul_f32_e32 v50, v50, v247
	v_mul_f32_e32 v51, v51, v162
	v_cvt_pk_bf16_f32 v162, v50, v51
	v_mul_f32_e32 v52, v52, v77
	v_mul_f32_e32 v53, v53, v77
	v_lshlrev_b32_e32 v247, 16, v163
	v_mul_f32_e32 v52, v110, v52
	v_mul_f32_e32 v53, v111, v53
	v_and_b32_e32 v163, 0xffff0000, v163
	v_mul_f32_e32 v52, v52, v247
	v_mul_f32_e32 v53, v53, v163
	v_cvt_pk_bf16_f32 v163, v52, v53
	s_nop 1
	v_permlane32_swap_b32_e32 v160, v162
	v_permlane32_swap_b32_e32 v161, v163
	global_store_dwordx4 v[244:245], v[160:163], off offset:64
	s_waitcnt vmcnt(7)
	v_permlane32_swap_b32_e32 v220, v222
	v_permlane32_swap_b32_e32 v221, v223
	v_mul_f32_e32 v75, v75, v77
	v_mul_f32_e32 v76, v76, v77
	v_lshlrev_b32_e32 v247, 16, v220
	v_mul_f32_e32 v75, v112, v75
	v_mul_f32_e32 v76, v113, v76
	v_and_b32_e32 v220, 0xffff0000, v220
	v_mul_f32_e32 v75, v75, v247
	v_mul_f32_e32 v76, v76, v220
	v_cvt_pk_bf16_f32 v220, v75, v76
	v_mul_f32_e32 v58, v58, v77
	v_mul_f32_e32 v59, v59, v77
	v_lshlrev_b32_e32 v247, 16, v221
	v_mul_f32_e32 v58, v114, v58
	v_mul_f32_e32 v59, v115, v59
	v_and_b32_e32 v221, 0xffff0000, v221
	v_mul_f32_e32 v58, v58, v247
	v_mul_f32_e32 v59, v59, v221
	v_cvt_pk_bf16_f32 v221, v58, v59
	v_mul_f32_e32 v54, v54, v77
	v_mul_f32_e32 v55, v55, v77
	v_lshlrev_b32_e32 v247, 16, v222
	v_mul_f32_e32 v54, v116, v54
	v_mul_f32_e32 v55, v117, v55
	v_and_b32_e32 v222, 0xffff0000, v222
	v_mul_f32_e32 v54, v54, v247
	v_mul_f32_e32 v55, v55, v222
	v_cvt_pk_bf16_f32 v222, v54, v55
	v_mul_f32_e32 v56, v56, v77
	v_mul_f32_e32 v57, v57, v77
	v_lshlrev_b32_e32 v247, 16, v223
	v_mul_f32_e32 v56, v118, v56
	v_mul_f32_e32 v57, v119, v57
	v_and_b32_e32 v223, 0xffff0000, v223
	v_mul_f32_e32 v56, v56, v247
	v_mul_f32_e32 v57, v57, v223
	v_cvt_pk_bf16_f32 v223, v56, v57
	s_nop 1
	v_permlane32_swap_b32_e32 v220, v222
	v_permlane32_swap_b32_e32 v221, v223
	global_store_dwordx4 v[244:245], v[220:223], off offset:96
	s_waitcnt vmcnt(7)
	v_permlane32_swap_b32_e32 v224, v226
	v_permlane32_swap_b32_e32 v225, v227
	v_mul_f32_e32 v62, v62, v77
	v_mul_f32_e32 v63, v63, v77
	v_lshlrev_b32_e32 v247, 16, v224
	v_mul_f32_e32 v62, v120, v62
	v_mul_f32_e32 v63, v121, v63
	v_and_b32_e32 v224, 0xffff0000, v224
	v_mul_f32_e32 v62, v62, v247
	v_mul_f32_e32 v63, v63, v224
	v_cvt_pk_bf16_f32 v224, v62, v63
	v_mul_f32_e32 v60, v60, v77
	v_mul_f32_e32 v61, v61, v77
	v_lshlrev_b32_e32 v247, 16, v225
	v_mul_f32_e32 v60, v122, v60
	v_mul_f32_e32 v61, v123, v61
	v_and_b32_e32 v225, 0xffff0000, v225
	v_mul_f32_e32 v60, v60, v247
	v_mul_f32_e32 v61, v61, v225
	v_cvt_pk_bf16_f32 v225, v60, v61
	v_mul_f32_e32 v34, v34, v77
	v_mul_f32_e32 v35, v35, v77
	v_lshlrev_b32_e32 v247, 16, v226
	v_mul_f32_e32 v34, v124, v34
	v_mul_f32_e32 v35, v125, v35
	v_and_b32_e32 v226, 0xffff0000, v226
	v_mul_f32_e32 v34, v34, v247
	v_mul_f32_e32 v35, v35, v226
	v_cvt_pk_bf16_f32 v226, v34, v35
	v_mul_f32_e32 v36, v36, v77
	v_mul_f32_e32 v37, v37, v77
	v_lshlrev_b32_e32 v247, 16, v227
	v_mul_f32_e32 v36, v126, v36
	v_mul_f32_e32 v37, v127, v37
	v_and_b32_e32 v227, 0xffff0000, v227
	v_mul_f32_e32 v36, v36, v247
	v_mul_f32_e32 v37, v37, v227
	v_cvt_pk_bf16_f32 v227, v36, v37
	s_nop 1
	v_permlane32_swap_b32_e32 v224, v226
	v_permlane32_swap_b32_e32 v225, v227
	global_store_dwordx4 v[244:245], v[224:227], off offset:128
	s_waitcnt vmcnt(7)
	v_permlane32_swap_b32_e32 v228, v230
	v_permlane32_swap_b32_e32 v229, v231
	v_mul_f32_e32 v64, v64, v77
	v_mul_f32_e32 v65, v65, v77
	v_lshlrev_b32_e32 v247, 16, v228
	v_mul_f32_e32 v64, v128, v64
	v_mul_f32_e32 v65, v129, v65
	v_and_b32_e32 v228, 0xffff0000, v228
	v_mul_f32_e32 v64, v64, v247
	v_mul_f32_e32 v65, v65, v228
	v_cvt_pk_bf16_f32 v228, v64, v65
	v_mul_f32_e32 v42, v42, v77
	v_mul_f32_e32 v43, v43, v77
	v_lshlrev_b32_e32 v247, 16, v229
	v_mul_f32_e32 v42, v130, v42
	v_mul_f32_e32 v43, v131, v43
	v_and_b32_e32 v229, 0xffff0000, v229
	v_mul_f32_e32 v42, v42, v247
	v_mul_f32_e32 v43, v43, v229
	v_cvt_pk_bf16_f32 v229, v42, v43
	v_mul_f32_e32 v38, v38, v77
	v_mul_f32_e32 v39, v39, v77
	v_lshlrev_b32_e32 v247, 16, v230
	v_mul_f32_e32 v38, v132, v38
	v_mul_f32_e32 v39, v133, v39
	v_and_b32_e32 v230, 0xffff0000, v230
	v_mul_f32_e32 v38, v38, v247
	v_mul_f32_e32 v39, v39, v230
	v_cvt_pk_bf16_f32 v230, v38, v39
	v_mul_f32_e32 v40, v40, v77
	v_mul_f32_e32 v41, v41, v77
	v_lshlrev_b32_e32 v247, 16, v231
	v_mul_f32_e32 v40, v134, v40
	v_mul_f32_e32 v41, v135, v41
	v_and_b32_e32 v231, 0xffff0000, v231
	v_mul_f32_e32 v40, v40, v247
	v_mul_f32_e32 v41, v41, v231
	v_cvt_pk_bf16_f32 v231, v40, v41
	s_nop 1
	v_permlane32_swap_b32_e32 v228, v230
	v_permlane32_swap_b32_e32 v229, v231
	global_store_dwordx4 v[244:245], v[228:231], off offset:160
	s_waitcnt vmcnt(7)
	v_permlane32_swap_b32_e32 v232, v234
	v_permlane32_swap_b32_e32 v233, v235
	v_mul_f32_e32 v46, v46, v77
	v_mul_f32_e32 v47, v47, v77
	v_lshlrev_b32_e32 v247, 16, v232
	v_mul_f32_e32 v46, v136, v46
	v_mul_f32_e32 v47, v137, v47
	v_and_b32_e32 v232, 0xffff0000, v232
	v_mul_f32_e32 v46, v46, v247
	v_mul_f32_e32 v47, v47, v232
	v_cvt_pk_bf16_f32 v232, v46, v47
	v_mul_f32_e32 v44, v44, v77
	v_mul_f32_e32 v45, v45, v77
	v_lshlrev_b32_e32 v247, 16, v233
	v_mul_f32_e32 v44, v138, v44
	v_mul_f32_e32 v45, v139, v45
	v_and_b32_e32 v233, 0xffff0000, v233
	v_mul_f32_e32 v44, v44, v247
	v_mul_f32_e32 v45, v45, v233
	v_cvt_pk_bf16_f32 v233, v44, v45
	v_mul_f32_e32 v18, v18, v77
	v_mul_f32_e32 v19, v19, v77
	v_lshlrev_b32_e32 v247, 16, v234
	v_mul_f32_e32 v18, v140, v18
	v_mul_f32_e32 v19, v141, v19
	v_and_b32_e32 v234, 0xffff0000, v234
	v_mul_f32_e32 v18, v18, v247
	v_mul_f32_e32 v19, v19, v234
	v_cvt_pk_bf16_f32 v234, v18, v19
	v_mul_f32_e32 v20, v20, v77
	v_mul_f32_e32 v21, v21, v77
	v_lshlrev_b32_e32 v247, 16, v235
	v_mul_f32_e32 v20, v142, v20
	v_mul_f32_e32 v21, v143, v21
	v_and_b32_e32 v235, 0xffff0000, v235
	v_mul_f32_e32 v20, v20, v247
	v_mul_f32_e32 v21, v21, v235
	v_cvt_pk_bf16_f32 v235, v20, v21
	s_nop 1
	v_permlane32_swap_b32_e32 v232, v234
	v_permlane32_swap_b32_e32 v233, v235
	global_store_dwordx4 v[244:245], v[232:235], off offset:192
	s_waitcnt vmcnt(7)
	v_permlane32_swap_b32_e32 v236, v238
	v_permlane32_swap_b32_e32 v237, v239
	v_mul_f32_e32 v26, v26, v77
	v_mul_f32_e32 v27, v27, v77
	v_lshlrev_b32_e32 v247, 16, v236
	v_mul_f32_e32 v26, v144, v26
	v_mul_f32_e32 v27, v145, v27
	v_and_b32_e32 v236, 0xffff0000, v236
	v_mul_f32_e32 v26, v26, v247
	v_mul_f32_e32 v27, v27, v236
	v_cvt_pk_bf16_f32 v236, v26, v27
	v_mul_f32_e32 v24, v24, v77
	v_mul_f32_e32 v25, v25, v77
	v_lshlrev_b32_e32 v247, 16, v237
	v_mul_f32_e32 v24, v146, v24
	v_mul_f32_e32 v25, v147, v25
	v_and_b32_e32 v237, 0xffff0000, v237
	v_mul_f32_e32 v24, v24, v247
	v_mul_f32_e32 v25, v25, v237
	v_cvt_pk_bf16_f32 v237, v24, v25
	v_mul_f32_e32 v22, v22, v77
	v_mul_f32_e32 v23, v23, v77
	v_lshlrev_b32_e32 v247, 16, v238
	v_mul_f32_e32 v22, v148, v22
	v_mul_f32_e32 v23, v149, v23
	v_and_b32_e32 v238, 0xffff0000, v238
	v_mul_f32_e32 v22, v22, v247
	v_mul_f32_e32 v23, v23, v238
	v_cvt_pk_bf16_f32 v238, v22, v23
	v_mul_f32_e32 v6, v6, v77
	v_mul_f32_e32 v7, v7, v77
	v_lshlrev_b32_e32 v247, 16, v239
	v_mul_f32_e32 v6, v150, v6
	v_mul_f32_e32 v7, v151, v7
	v_and_b32_e32 v239, 0xffff0000, v239
	v_mul_f32_e32 v6, v6, v247
	v_mul_f32_e32 v7, v7, v239
	v_cvt_pk_bf16_f32 v239, v6, v7
	s_nop 1
	v_permlane32_swap_b32_e32 v236, v238
	v_permlane32_swap_b32_e32 v237, v239
	global_store_dwordx4 v[244:245], v[236:239], off offset:224
